# P7 fused epilogue: second-half x1 rows loaded in the same round trip as the first half (one exposed HBM round trip less)
# baseline (speedup 1.0000x reference)
; __device__ __forceinline__ float bf_lo(unsigned u) { return __uint_as_float(u << 16); }
; __device__ __forceinline__ float bf_hi(unsigned u) { return __uint_as_float(u & 0xffff0000u); }
;     __device__ __forceinline__ void fused(f32x4 (&acc)[2][2][4][2], const Unit& u, int wr, int wc, int fr, int fq, float* smem) const {
;     ...
;         const float* mb = mod + (size_t)(u.pm >> 3) * NMOD;
;         const int cb = u.pn * BM + wc * 32 + 8 * fq, rl0 = wr * 64 + fr;
;         float* part = smem; float* rsv = smem + 1024;
;         f32x4 gt[2][2];
; #pragma unroll
;         for (int bj = 0; bj < 2; ++bj)
; #pragma unroll
;             for (int n = 0; n < 2; ++n) gt[bj][n] = *(const f32x4*)(mb + (MODE ? 5120 : 2048) + cb + bj * HALF + n * 4);
; #pragma unroll
;         for (int ai = 0; ai < 2; ++ai) {
;             f32x4 bs[4][2][2];
; #pragma unroll
;             for (int m = 0; m < 4; ++m) { const size_t ro = (size_t)(u.pm * BM + rl0 + ai * HALF + m * 16) * DM;
; #pragma unroll
;                 for (int bj = 0; bj < 2; ++bj)
; #pragma unroll
;                     for (int n = 0; n < 2; ++n) { const int c = cb + bj * HALF + n * 4;
;                         if (MODE) { const uint2 q = *(const uint2*)(X1 + ro + c); bs[m][bj][n] = (f32x4){bf_lo(q.x), bf_hi(q.x), bf_lo(q.y), bf_hi(q.y)}; }
;                         else bs[m][bj][n] = *(const f32x4*)(xp + ro + c); } }
;             __builtin_amdgcn_sched_barrier(0);
; #pragma unroll
;             for (int m = 0; m < 4; ++m) { float ss = 0.f;
; #pragma unroll
;                 for (int bj = 0; bj < 2; ++bj)
; #pragma unroll
;                     for (int n = 0; n < 2; ++n) { const f32x4 v = bs[m][bj][n] + gt[bj][n] * acc[ai][bj][m][n]; acc[ai][bj][m][n] = v; ss += v[0] * v[0] + v[1] * v[1] + v[2] * v[2] + v[3] * v[3]; }
;                 ss += __shfl_xor(ss, 16); ss += __shfl_xor(ss, 32);
;                 if (fq == 0) part[(rl0 + ai * HALF + m * 16) * 4 + wc] = ss; } }
.LBB0_781:
	s_ashr_i32 s0, s8, 3
	s_lshl_b32 s2, s35, 5
	s_mul_hi_i32 s1, s0, 0x6000
	s_mulk_i32 s0, 0x6000
	s_add_u32 s0, s16, s0
	s_addc_u32 s1, s17, s1
	s_lshl_b32 s3, s9, 8
	s_or_b32 s2, s3, s2
	v_lshl_or_b32 v170, v173, 3, s2
	v_ashrrev_i32_e32 v171, 31, v170
	v_lshl_add_u64 v[128:129], v[170:171], 2, s[0:1]
	s_mov_b64 s[0:1], 0x5000
	v_lshl_add_u64 v[132:133], v[128:129], 0, s[0:1]
	s_movk_i32 s0, 0x5000
	v_add_co_u32_e32 v128, vcc, s0, v128
	s_lshl_b32 s0, s8, 8
	v_add_u32_e32 v168, s0, v184
	v_ashrrev_i32_e32 v169, 31, v168
	v_lshlrev_b64 v[144:145], 11, v[168:169]
	v_lshl_add_u64 v[144:145], s[18:19], 0, v[144:145]
	v_lshlrev_b64 v[182:183], 1, v[170:171]
	v_mov_b32_e32 v172, v224
	v_addc_co_u32_e32 v129, vcc, 0, v129, vcc
	v_lshl_add_u64 v[144:145], v[144:145], 0, v[182:183]
	s_barrier
	global_load_dwordx4 v[140:143], v[128:129], off
	s_nop 0
	global_load_dwordx4 v[128:131], v[132:133], off offset:528
	global_load_dwordx4 v[136:139], v[132:133], off offset:16
	s_nop 0
	global_load_dwordx4 v[132:135], v[132:133], off offset:512
	s_nop 0
	global_load_dwordx4 v[174:177], v[144:145], off
	global_load_dwordx4 v[178:181], v[144:145], off offset:256
	v_or_b32_e32 v144, 16, v168
	v_ashrrev_i32_e32 v145, 31, v144
	v_lshlrev_b64 v[144:145], 11, v[144:145]
	v_lshl_add_u64 v[144:145], s[18:19], 0, v[144:145]
	v_lshl_add_u64 v[144:145], v[144:145], 0, v[182:183]
	global_load_dwordx4 v[164:167], v[144:145], off
	global_load_dwordx4 v[160:163], v[144:145], off offset:256
	v_or_b32_e32 v144, 32, v168
	v_ashrrev_i32_e32 v145, 31, v144
	v_lshlrev_b64 v[144:145], 11, v[144:145]
	v_lshl_add_u64 v[144:145], s[18:19], 0, v[144:145]
	v_lshl_add_u64 v[144:145], v[144:145], 0, v[182:183]
	global_load_dwordx4 v[156:159], v[144:145], off
	global_load_dwordx4 v[152:155], v[144:145], off offset:256
	v_or_b32_e32 v144, 48, v168
	v_ashrrev_i32_e32 v145, 31, v144
	v_lshlrev_b64 v[144:145], 11, v[144:145]
	v_lshl_add_u64 v[144:145], s[18:19], 0, v[144:145]
	v_lshl_add_u64 v[144:145], v[144:145], 0, v[182:183]
	global_load_dwordx4 v[148:151], v[144:145], off
	s_nop 0
	global_load_dwordx4 v[144:147], v[144:145], off offset:256
	v_add_u32_e32 v238, 0x80, v168
	v_ashrrev_i32_e32 v239, 31, v238
	v_lshlrev_b64 v[236:237], 11, v[238:239]
	v_lshl_add_u64 v[236:237], s[18:19], 0, v[236:237]
	v_lshl_add_u64 v[236:237], v[236:237], 0, v[182:183]
	s_mov_b64 s[2:3], 0x8000
	global_load_dwordx4 v[194:197], v[236:237], off
	global_load_dwordx4 v[198:201], v[236:237], off offset:256
	v_lshl_add_u64 v[236:237], v[236:237], 0, s[2:3]
	global_load_dwordx4 v[202:205], v[236:237], off
	global_load_dwordx4 v[206:209], v[236:237], off offset:256
	v_lshl_add_u64 v[236:237], v[236:237], 0, s[2:3]
	global_load_dwordx4 v[210:213], v[236:237], off
	global_load_dwordx4 v[214:217], v[236:237], off offset:256
	v_lshl_add_u64 v[236:237], v[236:237], 0, s[2:3]
	global_load_dwordx4 v[218:221], v[236:237], off
	global_load_dwordx4 v[232:235], v[236:237], off offset:256
	s_lshl_b32 s0, s35, 2
	s_add_i32 s0, s0, 16
	v_cmp_eq_u32_e32 vcc, 0, v173
	v_lshl_add_u32 v173, v184, 4, s0
	s_waitcnt vmcnt(0)
	v_lshlrev_b32_e32 v186, 16, v174
	v_and_b32_e32 v187, 0xffff0000, v174
	v_lshlrev_b32_e32 v174, 16, v175
	v_and_b32_e32 v175, 0xffff0000, v175
	v_lshlrev_b32_e32 v188, 16, v176
	v_and_b32_e32 v189, 0xffff0000, v176
	v_lshlrev_b32_e32 v176, 16, v177
	v_and_b32_e32 v177, 0xffff0000, v177
	v_lshlrev_b32_e32 v190, 16, v178
	v_and_b32_e32 v191, 0xffff0000, v178
	v_lshlrev_b32_e32 v178, 16, v179
	v_and_b32_e32 v179, 0xffff0000, v179
	v_lshlrev_b32_e32 v192, 16, v180
	v_and_b32_e32 v193, 0xffff0000, v180
	v_lshlrev_b32_e32 v180, 16, v181
	v_and_b32_e32 v181, 0xffff0000, v181
	v_pk_fma_f32 v[124:125], v[124:125], v[140:141], v[186:187]
	v_pk_fma_f32 v[120:121], v[120:121], v[136:137], v[188:189]
	v_pk_fma_f32 v[126:127], v[126:127], v[142:143], v[174:175]
	v_mul_f32_e32 v174, v125, v125
	v_mul_f32_e32 v175, v121, v121
	v_fmac_f32_e32 v174, v124, v124
	v_pk_fma_f32 v[122:123], v[122:123], v[138:139], v[176:177]
	v_fmac_f32_e32 v175, v120, v120
	v_fmac_f32_e32 v174, v126, v126
	v_fmac_f32_e32 v175, v122, v122
	v_fmac_f32_e32 v174, v127, v127
	v_fmac_f32_e32 v175, v123, v123
	v_pk_fma_f32 v[116:117], v[116:117], v[132:133], v[190:191]
	v_add_f32_e32 v174, v174, v175
	v_mul_f32_e32 v175, v117, v117
	v_pk_fma_f32 v[118:119], v[118:119], v[134:135], v[178:179]
	v_fmac_f32_e32 v175, v116, v116
	v_fmac_f32_e32 v175, v118, v118
	v_fmac_f32_e32 v175, v119, v119
	v_pk_fma_f32 v[112:113], v[112:113], v[128:129], v[192:193]
	v_add_f32_e32 v174, v174, v175
	v_mul_f32_e32 v175, v113, v113
	v_pk_fma_f32 v[114:115], v[114:115], v[130:131], v[180:181]
	v_fmac_f32_e32 v175, v112, v112
	v_fmac_f32_e32 v175, v114, v114
	v_fmac_f32_e32 v175, v115, v115
	v_add_f32_e32 v174, v174, v175
	ds_bpermute_b32 v175, v229, v174
	s_waitcnt lgkmcnt(0)
	v_add_f32_e32 v174, v174, v175
	ds_bpermute_b32 v175, v230, v174
	s_and_saveexec_b64 s[0:1], vcc
	s_cbranch_execz .LBB0_783
	s_waitcnt lgkmcnt(0)
	v_add_f32_e32 v174, v174, v175
	ds_write_b32 v173, v174

; __device__ __forceinline__ float bf_lo(unsigned u) { return __uint_as_float(u << 16); }
; __device__ __forceinline__ float bf_hi(unsigned u) { return __uint_as_float(u & 0xffff0000u); }
;     __device__ __forceinline__ void fused(f32x4 (&acc)[2][2][4][2], const Unit& u, int wr, int wc, int fr, int fq, float* smem) const {
;     ...
;             for (int m = 0; m < 4; ++m) { const size_t ro = (size_t)(u.pm * BM + rl0 + ai * HALF + m * 16) * DM;
; #pragma unroll
;                 for (int bj = 0; bj < 2; ++bj)
; #pragma unroll
;                     for (int n = 0; n < 2; ++n) { const int c = cb + bj * HALF + n * 4;
;                         if (MODE) { const uint2 q = *(const uint2*)(X1 + ro + c); bs[m][bj][n] = (f32x4){bf_lo(q.x), bf_hi(q.x), bf_lo(q.y), bf_hi(q.y)}; }
;                         else bs[m][bj][n] = *(const f32x4*)(xp + ro + c); } }
;             __builtin_amdgcn_sched_barrier(0);
; #pragma unroll
;             for (int m = 0; m < 4; ++m) { float ss = 0.f;
; #pragma unroll
;                 for (int bj = 0; bj < 2; ++bj)
; #pragma unroll
;                     for (int n = 0; n < 2; ++n) { const f32x4 v = bs[m][bj][n] + gt[bj][n] * acc[ai][bj][m][n]; acc[ai][bj][m][n] = v; ss += v[0] * v[0] + v[1] * v[1] + v[2] * v[2] + v[3] * v[3]; }
;                 ss += __shfl_xor(ss, 16); ss += __shfl_xor(ss, 32);
;                 if (fq == 0) part[(rl0 + ai * HALF + m * 16) * 4 + wc] = ss; } }
.LBB0_789:
	s_or_b64 exec, exec, s[0:1]
	v_add_u32_e32 v178, 0x80, v168
	v_ashrrev_i32_e32 v179, 31, v178
	s_waitcnt lgkmcnt(0)
	v_lshlrev_b64 v[64:65], 11, v[178:179]
	v_lshl_add_u64 v[64:65], s[18:19], 0, v[64:65]
	v_add_u32_e32 v144, 0x90, v168
	v_lshl_add_u64 v[64:65], v[64:65], 0, v[182:183]
	v_ashrrev_i32_e32 v145, 31, v144
	v_mov_b64_e32 v[186:187], v[194:195]
	v_mov_b64_e32 v[188:189], v[196:197]
	v_mov_b64_e32 v[190:191], v[198:199]
	v_mov_b64_e32 v[192:193], v[200:201]
	v_lshlrev_b64 v[64:65], 11, v[144:145]
	v_lshl_add_u64 v[64:65], s[18:19], 0, v[64:65]
	v_add_u32_e32 v90, 0xa0, v168
	v_lshl_add_u64 v[64:65], v[64:65], 0, v[182:183]
	v_ashrrev_i32_e32 v91, 31, v90
	v_mov_b64_e32 v[84:85], v[202:203]
	v_mov_b64_e32 v[86:87], v[204:205]
	v_mov_b64_e32 v[80:81], v[206:207]
	v_mov_b64_e32 v[82:83], v[208:209]
	v_lshlrev_b64 v[64:65], 11, v[90:91]
	v_lshl_add_u64 v[64:65], s[18:19], 0, v[64:65]
	v_add_u32_e32 v88, 0xb0, v168
	v_lshl_add_u64 v[64:65], v[64:65], 0, v[182:183]
	v_ashrrev_i32_e32 v89, 31, v88
	v_mov_b64_e32 v[76:77], v[210:211]
	v_mov_b64_e32 v[78:79], v[212:213]
	v_mov_b64_e32 v[72:73], v[214:215]
	v_mov_b64_e32 v[74:75], v[216:217]
	v_lshlrev_b64 v[64:65], 11, v[88:89]
	v_lshl_add_u64 v[64:65], s[18:19], 0, v[64:65]
	v_lshl_add_u64 v[64:65], v[64:65], 0, v[182:183]
	v_mov_b64_e32 v[68:69], v[218:219]
	v_mov_b64_e32 v[70:71], v[220:221]
	s_nop 0
	v_mov_b64_e32 v[64:65], v[232:233]
	v_mov_b64_e32 v[66:67], v[234:235]
	s_waitcnt vmcnt(7)
	v_lshlrev_b32_e32 v182, 16, v186
	v_and_b32_e32 v183, 0xffff0000, v186
	v_lshlrev_b32_e32 v186, 16, v187
	v_and_b32_e32 v187, 0xffff0000, v187
	v_lshlrev_b32_e32 v194, 16, v188
	v_and_b32_e32 v195, 0xffff0000, v188
	v_lshlrev_b32_e32 v188, 16, v189
	v_and_b32_e32 v189, 0xffff0000, v189
	s_waitcnt vmcnt(6)
	v_lshlrev_b32_e32 v196, 16, v190
	v_and_b32_e32 v197, 0xffff0000, v190
	v_lshlrev_b32_e32 v190, 16, v191
	v_and_b32_e32 v191, 0xffff0000, v191
	v_lshlrev_b32_e32 v198, 16, v192
	v_and_b32_e32 v199, 0xffff0000, v192
	v_lshlrev_b32_e32 v192, 16, v193
	v_and_b32_e32 v193, 0xffff0000, v193
	v_pk_fma_f32 v[60:61], v[60:61], v[140:141], v[182:183]
	v_pk_fma_f32 v[56:57], v[56:57], v[136:137], v[194:195]
	v_mul_f32_e32 v182, v61, v61
	v_mul_f32_e32 v183, v57, v57
	v_pk_fma_f32 v[62:63], v[62:63], v[142:143], v[186:187]
	v_fmac_f32_e32 v182, v60, v60
	v_pk_fma_f32 v[58:59], v[58:59], v[138:139], v[188:189]
	v_fmac_f32_e32 v183, v56, v56
	v_fmac_f32_e32 v182, v62, v62
	v_fmac_f32_e32 v183, v58, v58
	v_fmac_f32_e32 v182, v63, v63
	v_fmac_f32_e32 v183, v59, v59
	v_pk_fma_f32 v[52:53], v[52:53], v[132:133], v[196:197]
	v_add_f32_e32 v182, v182, v183
	v_mul_f32_e32 v183, v53, v53
	v_pk_fma_f32 v[54:55], v[54:55], v[134:135], v[190:191]
	v_fmac_f32_e32 v183, v52, v52
	v_fmac_f32_e32 v183, v54, v54
	v_fmac_f32_e32 v183, v55, v55
	v_pk_fma_f32 v[48:49], v[48:49], v[128:129], v[198:199]
	v_add_f32_e32 v182, v182, v183
	v_mul_f32_e32 v183, v49, v49
	v_pk_fma_f32 v[50:51], v[50:51], v[130:131], v[192:193]
	v_fmac_f32_e32 v183, v48, v48
	v_fmac_f32_e32 v183, v50, v50
	v_fmac_f32_e32 v183, v51, v51
	v_add_f32_e32 v182, v182, v183
	ds_bpermute_b32 v183, v229, v182
	s_waitcnt lgkmcnt(0)
	v_add_f32_e32 v182, v182, v183
	ds_bpermute_b32 v183, v230, v182
	s_and_saveexec_b64 s[0:1], vcc
	s_cbranch_execz .LBB0_791
	s_waitcnt lgkmcnt(0)
	v_add_f32_e32 v182, v182, v183
	ds_write_b32 v173, v182 offset:2048
